# NSA top-k threshold search: the two ballots of a step use different SGPR pairs and are issued back to back (was compare-count-compare-count on one pair)
# speedup vs baseline: 1.0865x; 1.0046x over previous
; DI void nsa_item(int wv0, PP p, int item, unsigned char* smem) {
;     ...
;     for (int qq = hp * 8; qq < hp * 8 + 8; ++qq) {
;       const float* ir = sImp0 + (16 * wv + qq) * 132;
;       const float i0 = ir[lane] + ir[64 * 132 + lane], i1 = ir[lane + 64] + ir[64 * 132 + lane + 64];
;       const unsigned k0 = v0 ? __float_as_uint(i0 + (f0 ? 1000.f : 0.f)) : 0u;
;       const unsigned k1 = v1 ? __float_as_uint(i1 + (f1 ? 1000.f : 0.f)) : 0u;
;       unsigned T = 0;
;     ...
;         const unsigned cand = T | (1u << bit);
;         const int cnt = __popcll(__ballot(k0 >= cand)) + __popcll(__ballot(k1 >= cand));
;         if (cnt >= 16) T = cand;
;       }
.LBB0_818:
	s_or_b64 exec, exec, s[10:11]
	s_waitcnt lgkmcnt(0)
	v_add_f32_e32 v8, v8, v9
	v_add_f32_e32 v8, v5, v8
	v_cndmask_b32_e64 v8, v8, 0, s[6:7]
	v_cmp_lt_u32_e64 s[18:19], s83, v7
	v_cmp_lt_u32_e64 s[10:11], s83, v8
	s_bcnt1_i32_b64 s12, s[18:19]
	s_bcnt1_i32_b64 s10, s[10:11]
	s_add_i32 s10, s10, s12
	s_cmp_gt_u32 s10, 15
	s_cselect_b32 s12, 2.0, 0
	s_or_b32 s13, s12, 0x20000000
	v_cmp_le_u32_e64 s[18:19], s13, v7
	v_cmp_le_u32_e64 s[10:11], s13, v8
	s_bcnt1_i32_b64 s14, s[18:19]
	s_bcnt1_i32_b64 s10, s[10:11]
	s_add_i32 s10, s10, s14
	s_cmp_gt_u32 s10, 15
	s_cselect_b32 s12, s13, s12
	s_or_b32 s13, s12, 0x10000000
	v_cmp_le_u32_e64 s[18:19], s13, v7
	v_cmp_le_u32_e64 s[10:11], s13, v8
	s_bcnt1_i32_b64 s14, s[18:19]
	s_bcnt1_i32_b64 s10, s[10:11]
	s_add_i32 s10, s10, s14
	s_cmp_gt_u32 s10, 15
	s_cselect_b32 s12, s13, s12
	s_or_b32 s13, s12, 0x8000000
	v_cmp_le_u32_e64 s[18:19], s13, v7
	v_cmp_le_u32_e64 s[10:11], s13, v8
	s_bcnt1_i32_b64 s14, s[18:19]
	s_bcnt1_i32_b64 s10, s[10:11]
	s_add_i32 s10, s10, s14
	s_cmp_gt_u32 s10, 15
	s_cselect_b32 s12, s13, s12
	s_or_b32 s13, s12, 0x4000000
	v_cmp_le_u32_e64 s[18:19], s13, v7
	v_cmp_le_u32_e64 s[10:11], s13, v8
	s_bcnt1_i32_b64 s14, s[18:19]
	s_bcnt1_i32_b64 s10, s[10:11]
	s_add_i32 s10, s10, s14
	s_cmp_gt_u32 s10, 15
	s_cselect_b32 s12, s13, s12
	s_or_b32 s13, s12, 0x2000000
	v_cmp_le_u32_e64 s[18:19], s13, v7
	v_cmp_le_u32_e64 s[10:11], s13, v8
	s_bcnt1_i32_b64 s14, s[18:19]
	s_bcnt1_i32_b64 s10, s[10:11]
	s_add_i32 s10, s10, s14
	s_cmp_gt_u32 s10, 15
	s_cselect_b32 s12, s13, s12
	s_or_b32 s13, s12, 0x1000000
	v_cmp_le_u32_e64 s[18:19], s13, v7
	v_cmp_le_u32_e64 s[10:11], s13, v8
	s_bcnt1_i32_b64 s14, s[18:19]
	s_bcnt1_i32_b64 s10, s[10:11]
	s_add_i32 s10, s10, s14
	s_cmp_gt_u32 s10, 15
	s_cselect_b32 s12, s13, s12
	s_or_b32 s13, s12, 0x800000
	v_cmp_le_u32_e64 s[18:19], s13, v7
	v_cmp_le_u32_e64 s[10:11], s13, v8
	s_bcnt1_i32_b64 s14, s[18:19]
	s_bcnt1_i32_b64 s10, s[10:11]
	s_add_i32 s10, s10, s14
	s_cmp_gt_u32 s10, 15
	s_cselect_b32 s12, s13, s12
	s_or_b32 s13, s12, 0x400000
	v_cmp_le_u32_e64 s[18:19], s13, v7
	v_cmp_le_u32_e64 s[10:11], s13, v8
	s_bcnt1_i32_b64 s14, s[18:19]
	s_bcnt1_i32_b64 s10, s[10:11]
	s_add_i32 s10, s10, s14
	s_cmp_gt_u32 s10, 15
	s_cselect_b32 s12, s13, s12
	s_or_b32 s13, s12, 0x200000
	v_cmp_le_u32_e64 s[18:19], s13, v7
	v_cmp_le_u32_e64 s[10:11], s13, v8
	s_bcnt1_i32_b64 s14, s[18:19]
	s_bcnt1_i32_b64 s10, s[10:11]
	s_add_i32 s10, s10, s14
	s_cmp_gt_u32 s10, 15
	s_cselect_b32 s12, s13, s12
	s_or_b32 s13, s12, 0x100000
	v_cmp_le_u32_e64 s[18:19], s13, v7
	v_cmp_le_u32_e64 s[10:11], s13, v8
	s_bcnt1_i32_b64 s14, s[18:19]
	s_bcnt1_i32_b64 s10, s[10:11]
	s_add_i32 s10, s10, s14
	s_cmp_gt_u32 s10, 15
	s_cselect_b32 s12, s13, s12
	s_or_b32 s13, s12, 0x80000
	v_cmp_le_u32_e64 s[18:19], s13, v7
	v_cmp_le_u32_e64 s[10:11], s13, v8
	s_bcnt1_i32_b64 s14, s[18:19]
	s_bcnt1_i32_b64 s10, s[10:11]
	s_add_i32 s10, s10, s14
	s_cmp_gt_u32 s10, 15
	s_cselect_b32 s12, s13, s12
	s_or_b32 s13, s12, 0x40000
	v_cmp_le_u32_e64 s[18:19], s13, v7
	v_cmp_le_u32_e64 s[10:11], s13, v8
	s_bcnt1_i32_b64 s14, s[18:19]
	s_bcnt1_i32_b64 s10, s[10:11]
	s_add_i32 s10, s10, s14
	s_cmp_gt_u32 s10, 15
	s_cselect_b32 s12, s13, s12
	s_or_b32 s13, s12, 0x20000
	v_cmp_le_u32_e64 s[18:19], s13, v7
	v_cmp_le_u32_e64 s[10:11], s13, v8
	s_bcnt1_i32_b64 s14, s[18:19]
	s_bcnt1_i32_b64 s10, s[10:11]
	s_add_i32 s10, s10, s14
	s_cmp_gt_u32 s10, 15
	s_cselect_b32 s12, s13, s12
	s_or_b32 s13, s12, 0x10000
	v_cmp_le_u32_e64 s[18:19], s13, v7
	v_cmp_le_u32_e64 s[10:11], s13, v8
	s_bcnt1_i32_b64 s14, s[18:19]
	s_bcnt1_i32_b64 s10, s[10:11]
	s_add_i32 s10, s10, s14
	s_cmp_gt_u32 s10, 15
	s_cselect_b32 s12, s13, s12
	s_or_b32 s13, s12, 0x8000
	v_cmp_le_u32_e64 s[18:19], s13, v7
	v_cmp_le_u32_e64 s[10:11], s13, v8
	s_bcnt1_i32_b64 s14, s[18:19]
	s_bcnt1_i32_b64 s10, s[10:11]
	s_add_i32 s10, s10, s14
	s_cmp_gt_u32 s10, 15
	s_cselect_b32 s12, s13, s12
	s_or_b32 s13, s12, 0x4000
	v_cmp_le_u32_e64 s[18:19], s13, v7
	v_cmp_le_u32_e64 s[10:11], s13, v8
	s_bcnt1_i32_b64 s14, s[18:19]
	s_bcnt1_i32_b64 s10, s[10:11]
	s_add_i32 s10, s10, s14
	s_cmp_gt_u32 s10, 15
	s_cselect_b32 s12, s13, s12
	s_or_b32 s13, s12, 0x2000
	v_cmp_le_u32_e64 s[18:19], s13, v7
	v_cmp_le_u32_e64 s[10:11], s13, v8
	s_bcnt1_i32_b64 s14, s[18:19]
	s_bcnt1_i32_b64 s10, s[10:11]
	s_add_i32 s10, s10, s14
	s_cmp_gt_u32 s10, 15
	s_cselect_b32 s12, s13, s12
; DI void nsa_item(int wv0, PP p, int item, unsigned char* smem) {
;     ...
;         const unsigned cand = T | (1u << bit);
;         const int cnt = __popcll(__ballot(k0 >= cand)) + __popcll(__ballot(k1 >= cand));
;         if (cnt >= 16) T = cand;
;       }
;       const bool g0 = k0 > T, g1 = k1 > T, e0 = k0 == T, e1 = k1 == T;
;       const int need = 16 - (__popcll(__ballot(g0)) + __popcll(__ballot(g1)));
;       const u64 be0 = __ballot(e0), be1 = __ballot(e1);
;       const int r0 = __popcll(be0 & ltm), r1 = __popcll(be0) + __popcll(be1 & ltm);
;       const u64 s0 = __ballot(v0 && (g0 || (e0 && r0 < need)));
;       const u64 s1 = __ballot(v1 && (g1 || (e1 && r1 < need)));
;       wlo |= s0;
;       whi |= s1;
;       if (lane == 0) { sSel[(16 * wv + qq) * 2] = s0; sSel[(16 * wv + qq) * 2 + 1] = s1; }
	s_or_b32 s13, s12, 0x1000
	v_cmp_le_u32_e64 s[18:19], s13, v7
	v_cmp_le_u32_e64 s[10:11], s13, v8
	s_bcnt1_i32_b64 s14, s[18:19]
	s_bcnt1_i32_b64 s10, s[10:11]
	s_add_i32 s10, s10, s14
	s_cmp_gt_u32 s10, 15
	s_cselect_b32 s12, s13, s12
	s_or_b32 s13, s12, 0x800
	v_cmp_le_u32_e64 s[18:19], s13, v7
	v_cmp_le_u32_e64 s[10:11], s13, v8
	s_bcnt1_i32_b64 s14, s[18:19]
	s_bcnt1_i32_b64 s10, s[10:11]
	s_add_i32 s10, s10, s14
	s_cmp_gt_u32 s10, 15
	s_cselect_b32 s12, s13, s12
	s_or_b32 s13, s12, 0x400
	v_cmp_le_u32_e64 s[18:19], s13, v7
	v_cmp_le_u32_e64 s[10:11], s13, v8
	s_bcnt1_i32_b64 s14, s[18:19]
	s_bcnt1_i32_b64 s10, s[10:11]
	s_add_i32 s10, s10, s14
	s_cmp_gt_u32 s10, 15
	s_cselect_b32 s12, s13, s12
	s_or_b32 s13, s12, 0x200
	v_cmp_le_u32_e64 s[18:19], s13, v7
	v_cmp_le_u32_e64 s[10:11], s13, v8
	s_bcnt1_i32_b64 s14, s[18:19]
	s_bcnt1_i32_b64 s10, s[10:11]
	s_add_i32 s10, s10, s14
	s_cmp_gt_u32 s10, 15
	s_cselect_b32 s12, s13, s12
	s_or_b32 s13, s12, 0x100
	v_cmp_le_u32_e64 s[18:19], s13, v7
	v_cmp_le_u32_e64 s[10:11], s13, v8
	s_bcnt1_i32_b64 s14, s[18:19]
	s_bcnt1_i32_b64 s10, s[10:11]
	s_add_i32 s10, s10, s14
	s_cmp_gt_u32 s10, 15
	s_cselect_b32 s12, s13, s12
	s_or_b32 s13, s12, 0x80
	v_cmp_le_u32_e64 s[18:19], s13, v7
	v_cmp_le_u32_e64 s[10:11], s13, v8
	s_bcnt1_i32_b64 s14, s[18:19]
	s_bcnt1_i32_b64 s10, s[10:11]
	s_add_i32 s10, s10, s14
	s_cmp_gt_u32 s10, 15
	s_cselect_b32 s12, s13, s12
	s_or_b32 s13, s12, 64
	v_cmp_le_u32_e64 s[18:19], s13, v7
	v_cmp_le_u32_e64 s[10:11], s13, v8
	s_bcnt1_i32_b64 s14, s[18:19]
	s_bcnt1_i32_b64 s10, s[10:11]
	s_add_i32 s10, s10, s14
	s_cmp_gt_u32 s10, 15
	s_cselect_b32 s12, s13, s12
	s_or_b32 s13, s12, 32
	v_cmp_le_u32_e64 s[18:19], s13, v7
	v_cmp_le_u32_e64 s[10:11], s13, v8
	s_bcnt1_i32_b64 s14, s[18:19]
	s_bcnt1_i32_b64 s10, s[10:11]
	s_add_i32 s10, s10, s14
	s_cmp_gt_u32 s10, 15
	s_cselect_b32 s12, s13, s12
	s_or_b32 s13, s12, 16
	v_cmp_le_u32_e64 s[18:19], s13, v7
	v_cmp_le_u32_e64 s[10:11], s13, v8
	s_bcnt1_i32_b64 s14, s[18:19]
	s_bcnt1_i32_b64 s10, s[10:11]
	s_add_i32 s10, s10, s14
	s_cmp_gt_u32 s10, 15
	s_cselect_b32 s12, s13, s12
	s_or_b32 s13, s12, 8
	v_cmp_le_u32_e64 s[18:19], s13, v7
	v_cmp_le_u32_e64 s[10:11], s13, v8
	s_bcnt1_i32_b64 s14, s[18:19]
	s_bcnt1_i32_b64 s10, s[10:11]
	s_add_i32 s10, s10, s14
	s_cmp_gt_u32 s10, 15
	s_cselect_b32 s12, s13, s12
	s_or_b32 s13, s12, 4
	v_cmp_le_u32_e64 s[18:19], s13, v7
	v_cmp_le_u32_e64 s[10:11], s13, v8
	s_bcnt1_i32_b64 s14, s[18:19]
	s_bcnt1_i32_b64 s10, s[10:11]
	s_add_i32 s10, s10, s14
	s_cmp_gt_u32 s10, 15
	s_cselect_b32 s12, s13, s12
	s_or_b32 s13, s12, 2
	v_cmp_le_u32_e64 s[18:19], s13, v7
	v_cmp_le_u32_e64 s[10:11], s13, v8
	s_bcnt1_i32_b64 s14, s[18:19]
	s_bcnt1_i32_b64 s10, s[10:11]
	s_add_i32 s10, s10, s14
	s_cmp_gt_u32 s10, 15
	s_cselect_b32 s12, s13, s12
	s_or_b32 s13, s12, 1
	v_cmp_le_u32_e64 s[18:19], s13, v7
	v_cmp_le_u32_e64 s[10:11], s13, v8
	s_bcnt1_i32_b64 s14, s[18:19]
	s_bcnt1_i32_b64 s10, s[10:11]
	s_add_i32 s10, s10, s14
	s_cmp_gt_u32 s10, 15
	s_cselect_b32 s16, s13, s12
	v_cmp_eq_u32_e64 s[14:15], s16, v7
	v_cmp_lt_u32_e64 s[10:11], s16, v7
	v_cmp_lt_u32_e64 s[12:13], s16, v8
	v_cmp_eq_u32_e64 s[16:17], s16, v8
	v_and_b32_e32 v8, s14, v2
	s_bcnt1_i32_b64 s18, s[10:11]
	s_bcnt1_i32_b64 s19, s[12:13]
	v_and_b32_e32 v7, s15, v3
	v_bcnt_u32_b32 v8, v8, 0
	v_and_b32_e32 v9, s16, v2
	s_add_i32 s18, s18, s19
	v_bcnt_u32_b32 v7, v7, v8
	v_and_b32_e32 v8, s17, v3
	v_bcnt_u32_b32 v9, v9, 0
	s_sub_i32 s26, 16, s18
	s_bcnt1_i32_b64 s18, s[14:15]
	v_bcnt_u32_b32 v8, v8, v9
	v_add_u32_e32 v8, s18, v8
	v_cmp_gt_i32_e64 s[18:19], s26, v7
	s_and_b64 s[14:15], s[14:15], s[18:19]
	v_cndmask_b32_e64 v7, 0, 1, s[14:15]
	v_cndmask_b32_e64 v9, 0, 1, s[4:5]
	s_or_b64 s[10:11], s[2:3], s[10:11]
	v_cndmask_b32_e64 v7, v7, v9, s[10:11]
	v_cmp_gt_i32_e64 s[10:11], s26, v8
	v_and_b32_e32 v7, 1, v7
	s_and_b64 s[10:11], s[16:17], s[10:11]
	v_cmp_ne_u32_e64 s[14:15], 0, v7
	v_cndmask_b32_e64 v7, 0, 1, s[10:11]
	v_cndmask_b32_e64 v8, 0, 1, s[8:9]
	s_or_b64 s[10:11], s[6:7], s[12:13]
	v_cndmask_b32_e64 v7, v7, v8, s[10:11]
	v_and_b32_e32 v7, 1, v7
	v_cmp_ne_u32_e64 s[10:11], 0, v7
	s_and_saveexec_b64 s[12:13], vcc
	s_cbranch_execz .LBB0_815
	s_add_i32 s16, s25, 32
	s_add_i32 s16, s16, 0x1e080
	v_mov_b32_e32 v8, s14
	v_mov_b32_e32 v9, s15
	v_mov_b32_e32 v10, s10
	v_mov_b32_e32 v11, s11
	v_mov_b32_e32 v7, s16
	ds_write_b128 v7, v[8:11]
	s_branch .LBB0_815
